# MLA units: K/V LDS-DMA issue split between the two wave groups (group B issues and waits for half of every tile)
# baseline (speedup 1.0000x reference)
.Lmla_fast_edge:
	s_add_i32 s7, s2, 1
	s_add_i32 s2, s86, 1
	s_cmp_lg_u32 s86, 2
	s_cselect_b32 s2, s2, 0
	s_add_i32 s95, s95, 64
	s_add_i32 s96, s96, 1
	s_mov_b64 s[4:5], 0x20000
	v_lshl_add_u64 v[178:179], v[178:179], 0, s[4:5]
	v_lshl_add_u64 v[180:181], v[180:181], 0, s[88:89]
	v_lshl_add_u64 v[182:183], v[182:183], 0, s[88:89]
	v_subrev_u32_e32 v177, 64, v177
	s_mov_b32 s10, s86
	s_mov_b32 s6, s72
	s_mov_b32 s86, s2
	s_mov_b32 s2, s7
	s_add_i32 s8, s97, s96
	s_add_i32 s7, s8, -2
	s_cmp_lt_i32 s7, 0
	s_cselect_b64 s[4:5], -1, 0
	s_cmp_le_i32 s95, s68
	s_cselect_b64 s[12:13], -1, 0
	s_or_b64 s[12:13], s[4:5], s[12:13]
	s_andn2_b64 s[4:5], exec, s[12:13]
	s_add_i32 s14, s8, -3
	s_cmp_gt_i32 s14, -1
	s_cselect_b64 s[14:15], -1, 0
	s_sub_i32 s20, s95, 64
	s_cmp_gt_i32 s20, s68
	s_cselect_b64 s[28:29], -1, 0
	s_and_b64 s[14:15], s[14:15], s[28:29]
	v_lshl_add_u32 v254, s6, 14, v202
	s_mov_b32 s72, s10
	s_mul_i32 s9, s72, 0x6000
	v_add_u32_e32 v0, s9, v193
	s_andn2_b64 vcc, exec, s[12:13]
	s_waitcnt vmcnt(5) lgkmcnt(0)
	s_barrier
	s_cbranch_vccnz .LBB0_528

.LBB0_531:
	s_cmp_lg_u64 s[80:81], 0
	s_cbranch_scc1 .Lmla_m_bar
	s_waitcnt vmcnt(0)
.Lmla_m_bar:
	s_waitcnt lgkmcnt(0)
	s_barrier
	s_andn2_b64 vcc, exec, s[80:81]
	s_cbranch_vccnz .Lmla_dma_b
	s_cmp_ge_i32 s96, s1
	s_cbranch_scc1 .Lmla_da_v
	s_mulk_i32 s6, 0x6000
	v_lshl_add_u64 v[2:3], s[66:67], 0, v[182:183]
	s_mov_b64 s[8:9], 0x17060000
	s_add_i32 s6, s69, s6
	v_lshl_add_u64 v[4:5], v[2:3], 0, s[8:9]
	s_mov_b32 m0, s6
	s_mov_b64 s[8:9], 0x1706c000
	global_load_lds_dwordx4 v[4:5], off
	v_lshl_add_u64 v[4:5], v[2:3], 0, s[8:9]
	s_add_i32 m0, s6, 0x1000
	s_mov_b64 s[8:9], 0x17060100
	global_load_lds_dwordx4 v[4:5], off
	v_lshl_add_u64 v[2:3], s[66:67], 0, v[180:181]
	v_lshl_add_u64 v[2:3], v[2:3], 0, s[8:9]
	s_add_i32 m0, s6, 0x4000
	s_nop 0
	global_load_lds_dwordx4 v[2:3], off
.Lmla_da_v:
	s_add_i32 s6, s96, -1
	s_cmp_ge_i32 s6, s1
	s_cbranch_scc1 .LBB0_536
	v_lshl_add_u64 v[2:3], s[66:67], 0, v[178:179]
	s_mov_b64 s[8:9], 0x1a020000
	s_lshl_b32 s6, s86, 14
	v_lshl_add_u64 v[4:5], v[2:3], 0, s[8:9]
	s_mov_b64 s[8:9], 0x1a028000
	s_add_i32 s6, s94, s6
	v_lshl_add_u64 v[2:3], v[2:3], 0, s[8:9]
	s_mov_b32 m0, s6
	s_nop 0
	global_load_lds_dwordx4 v[4:5], off
	s_add_i32 m0, s6, 0x1000
	s_nop 0
	global_load_lds_dwordx4 v[2:3], off
	s_branch .LBB0_536
.Lmla_dma_b:
	s_cmp_ge_i32 s96, s1
	s_cbranch_scc1 .Lmla_db_v
	s_mulk_i32 s6, 0x6000
	v_lshl_add_u64 v[2:3], s[66:67], 0, v[182:183]
	s_mov_b64 s[8:9], 0x17078000
	s_add_i32 s6, s69, s6
	v_lshl_add_u64 v[4:5], v[2:3], 0, s[8:9]
	s_add_i32 m0, s6, 0x1000
	s_mov_b64 s[8:9], 0x17084000
	global_load_lds_dwordx4 v[4:5], off
	v_lshl_add_u64 v[4:5], v[2:3], 0, s[8:9]
	s_add_i32 m0, s6, 0x2000
	s_mov_b64 s[8:9], 0x17078100
	global_load_lds_dwordx4 v[4:5], off
	v_lshl_add_u64 v[2:3], s[66:67], 0, v[180:181]
	v_lshl_add_u64 v[2:3], v[2:3], 0, s[8:9]
	s_add_i32 m0, s6, 0x4000
	s_nop 0
	global_load_lds_dwordx4 v[2:3], off
.Lmla_db_v:
	s_add_i32 s6, s96, -1
	s_cmp_ge_i32 s6, s1
	s_cbranch_scc1 .LBB0_536
	v_lshl_add_u64 v[2:3], s[66:67], 0, v[178:179]
	s_mov_b64 s[8:9], 0x1a030000
	s_lshl_b32 s6, s86, 14
	v_lshl_add_u64 v[4:5], v[2:3], 0, s[8:9]
	s_mov_b64 s[8:9], 0x1a038000
	s_add_i32 s6, s94, s6
	v_lshl_add_u64 v[2:3], v[2:3], 0, s[8:9]
	s_add_i32 m0, s6, 0x1000
	s_nop 0
	global_load_lds_dwordx4 v[4:5], off
	s_add_i32 m0, s6, 0x2000
	s_nop 0
	global_load_lds_dwordx4 v[2:3], off

.LBB0_545:
	s_andn2_b64 vcc, exec, s[4:5]
	s_cbranch_vccnz .LBB0_547
	s_waitcnt vmcnt(2) lgkmcnt(0)
	s_barrier

.LBB0_549:
	s_waitcnt vmcnt(5) lgkmcnt(0)
	s_barrier
	s_add_i32 s7, s2, 1
